# P6: per-row sumsq values for the epilogue's rmsnorm prefetched at the start of the unit's K-loop instead of at epilogue start
# speedup vs baseline: 1.0004x; 1.0004x over previous
; #define PG8_STAGE(bufoff, gbase, voff) do { _Pragma("unroll") for (int _i = 0; _i < 2; ++_i) \
;         __builtin_amdgcn_global_load_lds((const unsigned*)((const char*)(gbase) + (voff)[_i]), (PG8_LAS unsigned*)(lds + (bufoff) + ldsw + _i * 8192), 16, 0, 0); } while (0)
; #define PG8_LDA(dst, b, h) do { _Pragma("unroll") for (int m = 0; m < 4; ++m) _Pragma("unroll") for (int k = 0; k < 2; ++k) dst[m][k] = *(const PG8_LAS bf16x8*)(lds + PG8_SA(b, h) + aoff + m * 2048 + k * 1024); } while (0)
; #define PG8_LDB(dst, b, h) do { _Pragma("unroll") for (int n = 0; n < 2; ++n) _Pragma("unroll") for (int k = 0; k < 2; ++k) dst[n][k] = *(const PG8_LAS bf16x8*)(lds + PG8_SB(b, h) + boff + n * 2048 + k * 1024); } while (0)
; #define PG8_WAIT_V(n) asm volatile("s_waitcnt vmcnt(" #n ")" ::: "memory")
; #define PG8_WAIT_L(n) asm volatile("s_waitcnt lgkmcnt(" #n ")" ::: "memory")
; #define PG8_BAR __builtin_amdgcn_s_barrier()
; #define PG8_SCHED __builtin_amdgcn_sched_barrier(0)
; template <class Epi, class Sched, bool ALIGN_EPI = false, bool SP2 = false>
; __device__ __forceinline__ void gemm_phase(PG8_LAS unsigned char* lds, const Gemm g, const Sched& S, const Epi& E) {
;     ...
;         const bool has_next = S.next(ui + 1, nxt);
;         const char* nA = has_next ? (const char*)g.A + (size_t)nxt.pm * tstep : cA; const char* nB = has_next ? (const char*)g.Bt + (size_t)nxt.pn * tstep : cB;
;         for (int t = 0; t < nt; t += 2) {
;             const bool last = (t == nt - 2);
;             const char* a1 = cA + (size_t)(t + 1) * kstep;
;             const char* a2 = last ? nA : cA + (size_t)(t + 2) * kstep; const char* b2 = last ? nB : cB + (size_t)(t + 2) * kstep;
;             const char* a3 = a2 + kstep; const char* b3 = b2 + kstep;
;             if (last && has_next) S.a_ready(nxt);
;             if constexpr (SP2) {
;             PG8_LDB(B0, 0, 0); PG8_LDB(B1, 0, 1); PG8_SCHED; PG8_LDA(At, 0, 0); PG8_STAGE(PG8_SA(1, 1), a1 + hstep, voffA);
;             PG8_WAIT_V(8); PG8_WAIT_L(0); PG8_BAR; PG8_MMA(0, 0, At, B0); PG8_MMA(0, 1, At, B1); PG8_BAR; PG8_SCHED;
;     __device__ __forceinline__ void operator()(const f32x4 (&acc)[2][2][4][2], const pg8::Unit& u, int wr, int wc, int fr, int fq) const {
;     ...
;                 const float rs = sumsq ? rsqrtf(sumsq[row] * (1.f / 1024.f) + EPS) : 1.f;
.LBB0_781:
	s_ashr_i32 s17, s16, 31
	s_lshl_b64 s[18:19], s[16:17], 19
	s_add_u32 s18, s8, s18
	s_addc_u32 s19, s9, s19
	s_and_b64 s[20:21], s[4:5], exec
	s_cselect_b32 s17, s19, s23
	s_cselect_b32 s47, s18, s22
	s_ashr_i32 s15, s14, 31
	s_lshl_b64 s[20:21], s[14:15], 19
	s_add_u32 s20, s28, s20
	s_addc_u32 s21, s29, s21
	s_and_b64 s[26:27], s[4:5], exec
	s_cselect_b32 s15, s21, s25
	s_cselect_b32 s48, s20, s24
	s_add_u32 s22, s22, 0x40080
	s_addc_u32 s23, s23, 0
	s_add_u32 s49, s24, 0x100
	s_addc_u32 s50, s25, 0
	s_mov_b32 s51, -2
	v_lshl_add_u32 v244, s0, 8, v148
	v_ashrrev_i32_e32 v245, 31, v244
	v_lshl_add_u64 v[244:245], v[244:245], 2, s[10:11]
	global_load_dword v243, v[244:245], off
	global_load_dword v236, v[244:245], off offset:64
	global_load_dword v237, v[244:245], off offset:128
	global_load_dword v238, v[244:245], off offset:192
	global_load_dword v239, v[244:245], off offset:512
	global_load_dword v240, v[244:245], off offset:576
	global_load_dword v241, v[244:245], off offset:640
	global_load_dword v242, v[244:245], off offset:704
	ds_read_b128 v[144:147], v151
	ds_read_b128 v[156:159], v151 offset:1024
	ds_read_b128 v[160:163], v151 offset:2048
	ds_read_b128 v[164:167], v151 offset:3072
	ds_read_b128 v[168:171], v152
	ds_read_b128 v[172:175], v152 offset:1024
	ds_read_b128 v[176:179], v152 offset:2048
	ds_read_b128 v[180:183], v152 offset:3072
	s_add_u32 s24, s22, 0xfffc0080
	s_addc_u32 s25, s23, -1
	s_cmp_eq_u32 s51, 12
	s_cselect_b32 s27, s17, s25
	s_cselect_b32 s26, s47, s24
	s_cselect_b32 s25, s15, s50
	s_cselect_b32 s24, s48, s49
	v_lshl_add_u64 v[218:219], s[22:23], 0, v[136:137]
	s_add_i32 m0, s34, 0xc000
	ds_read_b128 v[184:187], v153
	ds_read_b128 v[190:193], v153 offset:1024
	ds_read_b128 v[194:197], v153 offset:2048
	ds_read_b128 v[198:201], v153 offset:3072
	ds_read_b128 v[202:205], v153 offset:4096
	ds_read_b128 v[206:209], v153 offset:5120
	ds_read_b128 v[210:213], v153 offset:6144
	ds_read_b128 v[214:217], v153 offset:7168
	global_load_lds_dwordx4 v[218:219], off
	v_lshl_add_u64 v[218:219], s[22:23], 0, v[138:139]
	s_add_i32 m0, s34, 0xe000
	s_nop 0
	global_load_lds_dwordx4 v[218:219], off
	s_waitcnt vmcnt(16)
	s_waitcnt lgkmcnt(0)
	s_barrier
	s_setprio 1
	v_mfma_f32_16x16x32_bf16 v[116:119], v[144:147], v[184:187], 0
	v_mfma_f32_16x16x32_bf16 v[112:115], v[160:163], v[184:187], 0
	v_mfma_f32_16x16x32_bf16 v[100:103], v[144:147], v[194:197], 0
	v_mfma_f32_16x16x32_bf16 v[96:99], v[160:163], v[194:197], 0
	v_mfma_f32_16x16x32_bf16 v[84:87], v[144:147], v[202:205], 0
	v_mfma_f32_16x16x32_bf16 v[80:83], v[160:163], v[202:205], 0
	v_mfma_f32_16x16x32_bf16 v[72:75], v[144:147], v[210:213], 0
	v_mfma_f32_16x16x32_bf16 v[64:67], v[160:163], v[210:213], 0
	v_mfma_f32_16x16x32_bf16 v[116:119], v[156:159], v[190:193], v[116:119]
	v_mfma_f32_16x16x32_bf16 v[112:115], v[164:167], v[190:193], v[112:115]
	v_mfma_f32_16x16x32_bf16 v[100:103], v[156:159], v[198:201], v[100:103]
	v_mfma_f32_16x16x32_bf16 v[96:99], v[164:167], v[198:201], v[96:99]
	v_mfma_f32_16x16x32_bf16 v[84:87], v[156:159], v[206:209], v[84:87]
	v_mfma_f32_16x16x32_bf16 v[80:83], v[164:167], v[206:209], v[80:83]
	v_mfma_f32_16x16x32_bf16 v[72:75], v[156:159], v[214:217], v[72:75]
	v_mfma_f32_16x16x32_bf16 v[64:67], v[164:167], v[214:217], v[64:67]
	v_mfma_f32_16x16x32_bf16 v[124:127], v[168:171], v[184:187], 0
	v_mfma_f32_16x16x32_bf16 v[120:123], v[176:179], v[184:187], 0
	v_mfma_f32_16x16x32_bf16 v[108:111], v[168:171], v[194:197], 0
	v_mfma_f32_16x16x32_bf16 v[104:107], v[176:179], v[194:197], 0
	v_mfma_f32_16x16x32_bf16 v[92:95], v[168:171], v[202:205], 0
	v_mfma_f32_16x16x32_bf16 v[88:91], v[176:179], v[202:205], 0
	v_mfma_f32_16x16x32_bf16 v[76:79], v[168:171], v[210:213], 0
	v_mfma_f32_16x16x32_bf16 v[68:71], v[176:179], v[210:213], 0
	v_mfma_f32_16x16x32_bf16 v[124:127], v[172:175], v[190:193], v[124:127]
	v_mfma_f32_16x16x32_bf16 v[120:123], v[180:183], v[190:193], v[120:123]
	v_mfma_f32_16x16x32_bf16 v[108:111], v[172:175], v[198:201], v[108:111]
	v_mfma_f32_16x16x32_bf16 v[104:107], v[180:183], v[198:201], v[104:107]
	v_mfma_f32_16x16x32_bf16 v[92:95], v[172:175], v[206:209], v[92:95]
	v_mfma_f32_16x16x32_bf16 v[88:91], v[180:183], v[206:209], v[88:91]
	v_mfma_f32_16x16x32_bf16 v[76:79], v[172:175], v[214:217], v[76:79]
	v_mfma_f32_16x16x32_bf16 v[68:71], v[180:183], v[214:217], v[68:71]
	s_setprio 0
	s_barrier
	s_add_i32 s52, s43, s30
	v_lshl_add_u64 v[218:219], s[24:25], 0, v[132:133]
	s_mov_b32 m0, s52
	ds_read_b128 v[184:187], v153 offset:16384
	ds_read_b128 v[190:193], v153 offset:17408
	ds_read_b128 v[194:197], v153 offset:18432
	ds_read_b128 v[198:201], v153 offset:19456
	ds_read_b128 v[202:205], v153 offset:20480
	ds_read_b128 v[206:209], v153 offset:21504
	ds_read_b128 v[210:213], v153 offset:22528
	ds_read_b128 v[214:217], v153 offset:23552
	global_load_lds_dwordx4 v[218:219], off
	s_add_i32 m0, s52, 0x2000
	s_add_u32 s52, s24, 0x40000
	v_lshl_add_u64 v[220:221], s[24:25], 0, v[128:129]
	s_addc_u32 s53, s25, 0
	s_add_i32 s54, s44, s30
	global_load_lds_dwordx4 v[220:221], off
	v_lshl_add_u64 v[222:223], s[52:53], 0, v[132:133]
	s_mov_b32 m0, s54
	v_lshl_add_u64 v[224:225], s[26:27], 0, v[130:131]
	global_load_lds_dwordx4 v[222:223], off
	v_lshl_add_u64 v[222:223], s[52:53], 0, v[128:129]
	s_add_i32 m0, s54, 0x2000
	s_nop 0
	global_load_lds_dwordx4 v[222:223], off
	v_lshl_add_u64 v[222:223], s[26:27], 0, v[134:135]
	s_mov_b32 m0, s34
	s_nop 0
	global_load_lds_dwordx4 v[222:223], off
	s_mov_b32 m0, s35
	s_nop 0
	global_load_lds_dwordx4 v[224:225], off
	s_waitcnt vmcnt(16)
	s_waitcnt lgkmcnt(0)
	s_barrier
; #define PG8_STAGE(bufoff, gbase, voff) do { _Pragma("unroll") for (int _i = 0; _i < 2; ++_i) \
;         __builtin_amdgcn_global_load_lds((const unsigned*)((const char*)(gbase) + (voff)[_i]), (PG8_LAS unsigned*)(lds + (bufoff) + ldsw + _i * 8192), 16, 0, 0); } while (0)
; #define PG8_LDA(dst, b, h) do { _Pragma("unroll") for (int m = 0; m < 4; ++m) _Pragma("unroll") for (int k = 0; k < 2; ++k) dst[m][k] = *(const PG8_LAS bf16x8*)(lds + PG8_SA(b, h) + aoff + m * 2048 + k * 1024); } while (0)
; #define PG8_LDB(dst, b, h) do { _Pragma("unroll") for (int n = 0; n < 2; ++n) _Pragma("unroll") for (int k = 0; k < 2; ++k) dst[n][k] = *(const PG8_LAS bf16x8*)(lds + PG8_SB(b, h) + boff + n * 2048 + k * 1024); } while (0)
; #define PG8_MMA(ai, bj, At, Bt) do { __builtin_amdgcn_s_setprio(1); _Pragma("unroll") for (int m = 0; m < 4; ++m) _Pragma("unroll") for (int n = 0; n < 2; ++n) _Pragma("unroll") for (int k = 0; k < 2; ++k) \
;         acc[ai][bj][m][n] = __builtin_amdgcn_mfma_f32_16x16x32_bf16(Bt[n][k], At[m][k], acc[ai][bj][m][n], 0, 0, 0); __builtin_amdgcn_s_setprio(0); } while (0)
; #define PG8_WAIT_V(n) asm volatile("s_waitcnt vmcnt(" #n ")" ::: "memory")
; #define PG8_WAIT_L(n) asm volatile("s_waitcnt lgkmcnt(" #n ")" ::: "memory")
; #define PG8_BAR __builtin_amdgcn_s_barrier()
; #define PG8_SCHED __builtin_amdgcn_sched_barrier(0)
; template <class Epi, class Sched, bool ALIGN_EPI = false, bool SP2 = false>
; __device__ __forceinline__ void gemm_phase(PG8_LAS unsigned char* lds, const Gemm g, const Sched& S, const Epi& E) {
;     ...
;             PG8_WAIT_V(8); PG8_WAIT_L(0); PG8_BAR; PG8_MMA(0, 0, At, B0); PG8_MMA(0, 1, At, B1); PG8_BAR; PG8_SCHED;
;             PG8_LDA(At, 0, 1); PG8_STAGE(PG8_SB(0, 0), b2, voffB); PG8_STAGE(PG8_SB(0, 1), b2 + hstep, voffB); PG8_STAGE(PG8_SA(0, 0), a2, voffA);
;             PG8_WAIT_V(8); PG8_WAIT_L(0); PG8_BAR; PG8_MMA(1, 0, At, B0); PG8_MMA(1, 1, At, B1); PG8_BAR; PG8_SCHED;
;             PG8_LDB(B0, 1, 0); PG8_LDB(B1, 1, 1); PG8_SCHED; PG8_LDA(At, 1, 0); PG8_STAGE(PG8_SA(0, 1), a2 + hstep, voffA);
;             PG8_WAIT_V(8); PG8_WAIT_L(0); PG8_BAR; PG8_MMA(0, 0, At, B0); PG8_MMA(0, 1, At, B1); PG8_BAR; PG8_SCHED;
	s_setprio 1
	v_mfma_f32_16x16x32_bf16 v[56:59], v[144:147], v[184:187], 0
	v_mfma_f32_16x16x32_bf16 v[48:51], v[160:163], v[184:187], 0
	v_mfma_f32_16x16x32_bf16 v[40:43], v[144:147], v[194:197], 0
	v_mfma_f32_16x16x32_bf16 v[32:35], v[160:163], v[194:197], 0
	v_mfma_f32_16x16x32_bf16 v[24:27], v[144:147], v[202:205], 0
	v_mfma_f32_16x16x32_bf16 v[16:19], v[160:163], v[202:205], 0
	v_mfma_f32_16x16x32_bf16 v[8:11], v[144:147], v[210:213], 0
	v_mfma_f32_16x16x32_bf16 v[0:3], v[160:163], v[210:213], 0
	v_mfma_f32_16x16x32_bf16 v[56:59], v[156:159], v[190:193], v[56:59]
	v_mfma_f32_16x16x32_bf16 v[48:51], v[164:167], v[190:193], v[48:51]
	v_mfma_f32_16x16x32_bf16 v[40:43], v[156:159], v[198:201], v[40:43]
	v_mfma_f32_16x16x32_bf16 v[32:35], v[164:167], v[198:201], v[32:35]
	v_mfma_f32_16x16x32_bf16 v[24:27], v[156:159], v[206:209], v[24:27]
	v_mfma_f32_16x16x32_bf16 v[16:19], v[164:167], v[206:209], v[16:19]
	v_mfma_f32_16x16x32_bf16 v[8:11], v[156:159], v[214:217], v[8:11]
	v_mfma_f32_16x16x32_bf16 v[0:3], v[164:167], v[214:217], v[0:3]
	v_mfma_f32_16x16x32_bf16 v[60:63], v[168:171], v[184:187], 0
	v_mfma_f32_16x16x32_bf16 v[52:55], v[176:179], v[184:187], 0
	v_mfma_f32_16x16x32_bf16 v[44:47], v[168:171], v[194:197], 0
	v_mfma_f32_16x16x32_bf16 v[36:39], v[176:179], v[194:197], 0
	v_mfma_f32_16x16x32_bf16 v[28:31], v[168:171], v[202:205], 0
	v_mfma_f32_16x16x32_bf16 v[20:23], v[176:179], v[202:205], 0
	v_mfma_f32_16x16x32_bf16 v[12:15], v[168:171], v[210:213], 0
	v_mfma_f32_16x16x32_bf16 v[4:7], v[176:179], v[210:213], 0
	v_mfma_f32_16x16x32_bf16 v[60:63], v[172:175], v[190:193], v[60:63]
	v_mfma_f32_16x16x32_bf16 v[52:55], v[180:183], v[190:193], v[52:55]
	v_mfma_f32_16x16x32_bf16 v[44:47], v[172:175], v[198:201], v[44:47]
	v_mfma_f32_16x16x32_bf16 v[36:39], v[180:183], v[198:201], v[36:39]
	v_mfma_f32_16x16x32_bf16 v[28:31], v[172:175], v[206:209], v[28:31]
	v_mfma_f32_16x16x32_bf16 v[20:23], v[180:183], v[206:209], v[20:23]
	v_mfma_f32_16x16x32_bf16 v[12:15], v[172:175], v[214:217], v[12:15]
	v_mfma_f32_16x16x32_bf16 v[4:7], v[180:183], v[214:217], v[4:7]
	s_setprio 0
	s_barrier
	s_add_i32 s52, 0, 0x18000
	v_add_u32_e32 v155, s52, v149
	s_add_i32 s53, 0, 0x1c000
	ds_read_b128 v[144:147], v155
	ds_read_b128 v[156:159], v155 offset:1024
	ds_read_b128 v[160:163], v155 offset:2048
	ds_read_b128 v[164:167], v155 offset:3072
	v_add_u32_e32 v155, s53, v149
	ds_read_b128 v[168:171], v155
	ds_read_b128 v[172:175], v155 offset:1024
	ds_read_b128 v[176:179], v155 offset:2048
	ds_read_b128 v[180:183], v155 offset:3072
	s_add_u32 s26, s26, 0x40000
	s_addc_u32 s27, s27, 0
	s_mov_b32 m0, s36
	v_lshl_add_u64 v[226:227], s[26:27], 0, v[134:135]
	ds_read_b128 v[184:187], v153 offset:32768
	ds_read_b128 v[190:193], v153 offset:33792
	ds_read_b128 v[194:197], v153 offset:34816
	ds_read_b128 v[198:201], v153 offset:35840
	ds_read_b128 v[202:205], v153 offset:36864
	ds_read_b128 v[206:209], v153 offset:37888
	ds_read_b128 v[210:213], v153 offset:38912
	ds_read_b128 v[214:217], v153 offset:39936
	global_load_lds_dwordx4 v[226:227], off
	v_lshl_add_u64 v[226:227], s[26:27], 0, v[130:131]
	s_mov_b32 m0, s37
	s_nop 0
	global_load_lds_dwordx4 v[226:227], off
	s_waitcnt vmcnt(8)
	s_waitcnt lgkmcnt(0)
	s_barrier
	s_setprio 1
	v_mfma_f32_16x16x32_bf16 v[116:119], v[144:147], v[184:187], v[116:119]
	v_mfma_f32_16x16x32_bf16 v[112:115], v[160:163], v[184:187], v[112:115]
	v_mfma_f32_16x16x32_bf16 v[100:103], v[144:147], v[194:197], v[100:103]
	v_mfma_f32_16x16x32_bf16 v[96:99], v[160:163], v[194:197], v[96:99]
	v_mfma_f32_16x16x32_bf16 v[84:87], v[144:147], v[202:205], v[84:87]
	v_mfma_f32_16x16x32_bf16 v[80:83], v[160:163], v[202:205], v[80:83]
	v_mfma_f32_16x16x32_bf16 v[72:75], v[144:147], v[210:213], v[72:75]
	v_mfma_f32_16x16x32_bf16 v[64:67], v[160:163], v[210:213], v[64:67]
	v_mfma_f32_16x16x32_bf16 v[116:119], v[156:159], v[190:193], v[116:119]
	v_mfma_f32_16x16x32_bf16 v[112:115], v[164:167], v[190:193], v[112:115]
	v_mfma_f32_16x16x32_bf16 v[100:103], v[156:159], v[198:201], v[100:103]
	v_mfma_f32_16x16x32_bf16 v[96:99], v[164:167], v[198:201], v[96:99]
	v_mfma_f32_16x16x32_bf16 v[84:87], v[156:159], v[206:209], v[84:87]
	v_mfma_f32_16x16x32_bf16 v[80:83], v[164:167], v[206:209], v[80:83]
	v_mfma_f32_16x16x32_bf16 v[72:75], v[156:159], v[214:217], v[72:75]
	v_mfma_f32_16x16x32_bf16 v[64:67], v[164:167], v[214:217], v[64:67]
	v_mfma_f32_16x16x32_bf16 v[124:127], v[168:171], v[184:187], v[124:127]
	v_mfma_f32_16x16x32_bf16 v[120:123], v[176:179], v[184:187], v[120:123]
	v_mfma_f32_16x16x32_bf16 v[108:111], v[168:171], v[194:197], v[108:111]
	v_mfma_f32_16x16x32_bf16 v[104:107], v[176:179], v[194:197], v[104:107]
	v_mfma_f32_16x16x32_bf16 v[92:95], v[168:171], v[202:205], v[92:95]
	v_mfma_f32_16x16x32_bf16 v[88:91], v[176:179], v[202:205], v[88:91]
	v_mfma_f32_16x16x32_bf16 v[76:79], v[168:171], v[210:213], v[76:79]
	v_mfma_f32_16x16x32_bf16 v[68:71], v[176:179], v[210:213], v[68:71]
	v_mfma_f32_16x16x32_bf16 v[124:127], v[172:175], v[190:193], v[124:127]
	v_mfma_f32_16x16x32_bf16 v[120:123], v[180:183], v[190:193], v[120:123]
	v_mfma_f32_16x16x32_bf16 v[108:111], v[172:175], v[198:201], v[108:111]
	v_mfma_f32_16x16x32_bf16 v[104:107], v[180:183], v[198:201], v[104:107]
	v_mfma_f32_16x16x32_bf16 v[92:95], v[172:175], v[206:209], v[92:95]
	v_mfma_f32_16x16x32_bf16 v[88:91], v[180:183], v[206:209], v[88:91]
	v_mfma_f32_16x16x32_bf16 v[76:79], v[172:175], v[214:217], v[76:79]
	v_mfma_f32_16x16x32_bf16 v[68:71], v[180:183], v[214:217], v[68:71]
	s_setprio 0
	s_barrier
; #define PG8_STAGE(bufoff, gbase, voff) do { _Pragma("unroll") for (int _i = 0; _i < 2; ++_i) \
;         __builtin_amdgcn_global_load_lds((const unsigned*)((const char*)(gbase) + (voff)[_i]), (PG8_LAS unsigned*)(lds + (bufoff) + ldsw + _i * 8192), 16, 0, 0); } while (0)
; #define PG8_LDA(dst, b, h) do { _Pragma("unroll") for (int m = 0; m < 4; ++m) _Pragma("unroll") for (int k = 0; k < 2; ++k) dst[m][k] = *(const PG8_LAS bf16x8*)(lds + PG8_SA(b, h) + aoff + m * 2048 + k * 1024); } while (0)
; #define PG8_MMA(ai, bj, At, Bt) do { __builtin_amdgcn_s_setprio(1); _Pragma("unroll") for (int m = 0; m < 4; ++m) _Pragma("unroll") for (int n = 0; n < 2; ++n) _Pragma("unroll") for (int k = 0; k < 2; ++k) \
;         acc[ai][bj][m][n] = __builtin_amdgcn_mfma_f32_16x16x32_bf16(Bt[n][k], At[m][k], acc[ai][bj][m][n], 0, 0, 0); __builtin_amdgcn_s_setprio(0); } while (0)
; #define PG8_WAIT_V(n) asm volatile("s_waitcnt vmcnt(" #n ")" ::: "memory")
; #define PG8_WAIT_L(n) asm volatile("s_waitcnt lgkmcnt(" #n ")" ::: "memory")
; #define PG8_BAR __builtin_amdgcn_s_barrier()
; #define PG8_SCHED __builtin_amdgcn_sched_barrier(0)
; template <class Epi, class Sched, bool ALIGN_EPI = false, bool SP2 = false>
; __device__ __forceinline__ void gemm_phase(PG8_LAS unsigned char* lds, const Gemm g, const Sched& S, const Epi& E) {
;     ...
;             PG8_LDA(At, 1, 1); PG8_STAGE(PG8_SB(1, 0), b3, voffB); PG8_STAGE(PG8_SB(1, 1), b3 + hstep, voffB); PG8_STAGE(PG8_SA(1, 0), a3, voffA);
;             PG8_WAIT_V(8); PG8_WAIT_L(0); PG8_BAR; PG8_MMA(1, 0, At, B0); PG8_MMA(1, 1, At, B1); PG8_BAR; PG8_SCHED;
	s_add_i32 s26, s52, s30
	v_lshl_add_u64 v[218:219], v[218:219], 0, s[6:7]
	s_mov_b32 m0, s26
	ds_read_b128 v[184:187], v153 offset:49152
	ds_read_b128 v[190:193], v153 offset:50176
	ds_read_b128 v[194:197], v153 offset:51200
	ds_read_b128 v[198:201], v153 offset:52224
	ds_read_b128 v[202:205], v153 offset:53248
	ds_read_b128 v[206:209], v153 offset:54272
	ds_read_b128 v[210:213], v153 offset:55296
	ds_read_b128 v[214:217], v153 offset:56320
	global_load_lds_dwordx4 v[218:219], off
	s_add_i32 m0, s26, 0x2000
	s_add_u32 s24, s24, 0x40080
	v_lshl_add_u64 v[218:219], v[220:221], 0, s[6:7]
	s_addc_u32 s25, s25, 0
	s_add_i32 s26, s53, s30
	global_load_lds_dwordx4 v[218:219], off
	v_lshl_add_u64 v[218:219], s[24:25], 0, v[132:133]
	s_mov_b32 m0, s26
	s_nop 0
	global_load_lds_dwordx4 v[218:219], off
	v_lshl_add_u64 v[218:219], s[24:25], 0, v[128:129]
	s_add_i32 m0, s26, 0x2000
	s_nop 0
	global_load_lds_dwordx4 v[218:219], off
	v_lshl_add_u64 v[218:219], v[222:223], 0, s[6:7]
	s_mov_b32 m0, s39
	s_nop 0
	global_load_lds_dwordx4 v[218:219], off
	v_lshl_add_u64 v[218:219], v[224:225], 0, s[6:7]
	s_mov_b32 m0, s40
	s_nop 0
	global_load_lds_dwordx4 v[218:219], off
	s_waitcnt vmcnt(8)
	s_waitcnt lgkmcnt(0)
	s_barrier
	s_setprio 1
	v_mfma_f32_16x16x32_bf16 v[56:59], v[144:147], v[184:187], v[56:59]
	v_mfma_f32_16x16x32_bf16 v[48:51], v[160:163], v[184:187], v[48:51]
	v_mfma_f32_16x16x32_bf16 v[40:43], v[144:147], v[194:197], v[40:43]
	v_mfma_f32_16x16x32_bf16 v[32:35], v[160:163], v[194:197], v[32:35]
	v_mfma_f32_16x16x32_bf16 v[24:27], v[144:147], v[202:205], v[24:27]
	v_mfma_f32_16x16x32_bf16 v[16:19], v[160:163], v[202:205], v[16:19]
	v_mfma_f32_16x16x32_bf16 v[8:11], v[144:147], v[210:213], v[8:11]
	v_mfma_f32_16x16x32_bf16 v[0:3], v[160:163], v[210:213], v[0:3]
	v_mfma_f32_16x16x32_bf16 v[56:59], v[156:159], v[190:193], v[56:59]
	v_mfma_f32_16x16x32_bf16 v[48:51], v[164:167], v[190:193], v[48:51]
	v_mfma_f32_16x16x32_bf16 v[40:43], v[156:159], v[198:201], v[40:43]
	v_mfma_f32_16x16x32_bf16 v[32:35], v[164:167], v[198:201], v[32:35]
	v_mfma_f32_16x16x32_bf16 v[24:27], v[156:159], v[206:209], v[24:27]
	v_mfma_f32_16x16x32_bf16 v[16:19], v[164:167], v[206:209], v[16:19]
	v_mfma_f32_16x16x32_bf16 v[8:11], v[156:159], v[214:217], v[8:11]
	v_mfma_f32_16x16x32_bf16 v[0:3], v[164:167], v[214:217], v[0:3]
	v_mfma_f32_16x16x32_bf16 v[60:63], v[168:171], v[184:187], v[60:63]
	v_mfma_f32_16x16x32_bf16 v[52:55], v[176:179], v[184:187], v[52:55]
	v_mfma_f32_16x16x32_bf16 v[44:47], v[168:171], v[194:197], v[44:47]
	v_mfma_f32_16x16x32_bf16 v[36:39], v[176:179], v[194:197], v[36:39]
	v_mfma_f32_16x16x32_bf16 v[28:31], v[168:171], v[202:205], v[28:31]
	v_mfma_f32_16x16x32_bf16 v[20:23], v[176:179], v[202:205], v[20:23]
	v_mfma_f32_16x16x32_bf16 v[12:15], v[168:171], v[210:213], v[12:15]
	v_mfma_f32_16x16x32_bf16 v[4:7], v[176:179], v[210:213], v[4:7]
	v_mfma_f32_16x16x32_bf16 v[60:63], v[172:175], v[190:193], v[60:63]
	v_mfma_f32_16x16x32_bf16 v[52:55], v[180:183], v[190:193], v[52:55]
	v_mfma_f32_16x16x32_bf16 v[44:47], v[172:175], v[198:201], v[44:47]
	v_mfma_f32_16x16x32_bf16 v[36:39], v[180:183], v[198:201], v[36:39]
	v_mfma_f32_16x16x32_bf16 v[28:31], v[172:175], v[206:209], v[28:31]
	v_mfma_f32_16x16x32_bf16 v[20:23], v[180:183], v[206:209], v[20:23]
	v_mfma_f32_16x16x32_bf16 v[12:15], v[172:175], v[214:217], v[12:15]
	v_mfma_f32_16x16x32_bf16 v[4:7], v[180:183], v[214:217], v[4:7]
	s_setprio 0
	s_barrier
	s_add_i32 s51, s51, 2
	s_add_u32 s22, s22, 0x100
	s_addc_u32 s23, s23, 0
	s_add_u32 s49, s49, 0x100
	s_addc_u32 s50, s50, 0

; __device__ __forceinline__ unsigned pk2(float lo, float hi) { return pg8::cvt_pk_bf16(lo, hi); }
; __device__ __forceinline__ float silu_f(float x) { return x * sigmoid_f(x); }
;     __device__ __forceinline__ void operator()(const f32x4 (&acc)[2][2][4][2], const pg8::Unit& u, int wr, int wc, int fr, int fq) const {
;         const int row0 = u.pm * 256 + wr * 64 + fr, col = u.pn * 128 + wc * 32 + 8 * fq;
; #pragma unroll
;         for (int ai = 0; ai < 2; ++ai)
; #pragma unroll
;             for (int m = 0; m < 4; ++m) {
;                 const int row = row0 + ai * 128 + m * 16;
;                 const float rs = sumsq ? rsqrtf(sumsq[row] * (1.f / 1024.f) + EPS) : 1.f;
;                 float o[8];
; #pragma unroll
;                 for (int n = 0; n < 2; ++n)
; #pragma unroll
;                     for (int e = 0; e < 4; ++e) { const float g = acc[ai][0][m][n][e] * rs, up = acc[ai][1][m][n][e] * rs; o[4 * n + e] = silu_f(g) * up; }
;                 u32x4 w; w.x = pk2(o[0], o[1]); w.y = pk2(o[2], o[3]); w.z = pk2(o[4], o[5]); w.w = pk2(o[6], o[7]);
;                 *(u32x4*)(H + (size_t)row * DFF + col) = w;
.LBB0_785:
	v_lshl_add_u32 v144, s0, 8, v148
	v_ashrrev_i32_e32 v145, 31, v144
	v_lshl_add_u64 v[146:147], v[144:145], 2, s[10:11]
	s_nop 0
	s_nop 0
	s_nop 0
	s_nop 0
	s_nop 0
	s_nop 0
	s_nop 0
	s_nop 0
	v_lshl_or_b32 v156, s1, 7, v150
	v_readlane_b32 s0, v235, 33
	v_mov_b32_e32 v161, v114
	v_mov_b32_e32 v114, v123
	v_readlane_b32 s1, v235, 34
	v_mov_b32_e32 v158, v124
	v_mov_b32_e32 v159, v116
	v_mov_b32_e32 v116, v125
	v_mov_b32_e32 v124, v126
	v_mov_b32_e32 v125, v118
	v_mov_b32_e32 v118, v127
	v_mov_b32_e32 v126, v120
	v_mov_b32_e32 v127, v112
	v_mov_b32_e32 v112, v121
	v_mov_b32_e32 v160, v122
	v_mov_b64_e32 v[120:121], s[0:1]
	v_ashrrev_i32_e32 v157, 31, v156
	v_or_b32_e32 v164, 16, v144
	v_mad_i64_i32 v[162:163], s[0:1], v144, s46, v[120:121]
	v_lshlrev_b64 v[122:123], 1, v[156:157]
	v_ashrrev_i32_e32 v165, 31, v164
	v_lshl_add_u64 v[156:157], v[162:163], 0, v[122:123]
	v_lshl_add_u64 v[162:163], v[164:165], 2, s[10:11]
	s_waitcnt vmcnt(0)
	v_mov_b32_e32 v145, v243
	v_fmamk_f32 v145, v145, 0x3a800000, v154
	v_mul_f32_e32 v155, 0x4b800000, v145
	v_cmp_gt_f32_e32 vcc, s45, v145
	s_nop 1
	v_cndmask_b32_e32 v145, v145, v155, vcc
	v_rsq_f32_e32 v145, v145
	s_nop 0
	v_mul_f32_e32 v155, 0x45800000, v145
	v_cndmask_b32_e32 v166, v145, v155, vcc
	v_pk_mul_f32 v[114:115], v[114:115], v[166:167] op_sel_hi:[1,0]
	v_pk_mul_f32 v[158:159], v[158:159], v[166:167] op_sel_hi:[1,0]
	v_pk_mul_f32 v[116:117], v[116:117], v[166:167] op_sel_hi:[1,0]
	v_pk_mul_f32 v[124:125], v[124:125], v[166:167] op_sel_hi:[1,0]
	v_pk_mul_f32 v[118:119], v[118:119], v[166:167] op_sel_hi:[1,0]
	v_pk_mul_f32 v[126:127], v[126:127], v[166:167] op_sel_hi:[1,0]
	v_pk_mul_f32 v[112:113], v[112:113], v[166:167] op_sel_hi:[1,0]
	v_pk_mul_f32 v[160:161], v[160:161], v[166:167] op_sel_hi:[1,0]
	v_mul_f32_e32 v170, 0xbfb8aa3b, v115
	v_mul_f32_e32 v145, 0xbfb8aa3b, v159
	v_mul_f32_e32 v155, 0xbfb8aa3b, v117
	v_mul_f32_e32 v165, 0xbfb8aa3b, v125
	v_mul_f32_e32 v166, 0xbfb8aa3b, v119
	v_mul_f32_e32 v167, 0xbfb8aa3b, v127
	v_mul_f32_e32 v168, 0xbfb8aa3b, v113
	v_mul_f32_e32 v169, 0xbfb8aa3b, v161
	v_exp_f32_e32 v170, v170
	v_exp_f32_e32 v145, v145
	v_exp_f32_e32 v155, v155
	v_exp_f32_e32 v165, v165
	v_exp_f32_e32 v166, v166
	v_exp_f32_e32 v167, v167
	v_exp_f32_e32 v168, v168
	v_exp_f32_e32 v169, v169
	v_add_f32_e32 v170, 1.0, v170
	v_add_f32_e32 v145, 1.0, v145
	v_add_f32_e32 v155, 1.0, v155
	v_add_f32_e32 v165, 1.0, v165
	v_add_f32_e32 v166, 1.0, v166
	v_add_f32_e32 v167, 1.0, v167
	v_add_f32_e32 v168, 1.0, v168
	v_add_f32_e32 v169, 1.0, v169
	v_rcp_f32_e32 v170, v170
	v_rcp_f32_e32 v145, v145
	v_rcp_f32_e32 v155, v155
	v_rcp_f32_e32 v165, v165
	v_rcp_f32_e32 v166, v166
	v_rcp_f32_e32 v167, v167
	v_rcp_f32_e32 v168, v168
	v_rcp_f32_e32 v169, v169
	v_mul_f32_e32 v115, v115, v170
	v_mul_f32_e32 v145, v159, v145
	v_mul_f32_e32 v117, v117, v155
	v_mul_f32_e32 v125, v125, v165
	v_mul_f32_e32 v119, v119, v166
	v_mul_f32_e32 v127, v127, v167
	v_mul_f32_e32 v113, v113, v168
	v_mul_f32_e32 v155, v161, v169
	v_mul_f32_e32 v115, v114, v115
	v_mul_f32_e32 v145, v158, v145
	v_mul_f32_e32 v116, v116, v117
	v_mul_f32_e32 v117, v124, v125
	v_mul_f32_e32 v118, v118, v119
	v_mul_f32_e32 v119, v126, v127
	v_mul_f32_e32 v124, v112, v113
	v_mul_f32_e32 v125, v160, v155
	v_cvt_pk_bf16_f32 v112, v145, v116
	v_cvt_pk_bf16_f32 v113, v117, v118
	v_cvt_pk_bf16_f32 v114, v119, v124
	v_cvt_pk_bf16_f32 v115, v125, v115
	global_store_dwordx4 v[156:157], v[112:115], off
	s_nop 0
	s_nop 0
	v_mov_b32_e32 v113, v100
	v_mov_b32_e32 v100, v109
	v_mov_b32_e32 v109, v102
	v_mov_b32_e32 v102, v111
	v_mov_b32_e32 v111, v96
	v_mov_b32_e32 v96, v105
	v_mov_b32_e32 v105, v98
	v_mov_b32_e32 v98, v107
	v_mov_b32_e32 v112, v108
	v_mov_b32_e32 v108, v110
	v_mov_b32_e32 v110, v104
	v_mov_b32_e32 v104, v106
	v_or_b32_e32 v106, 32, v144
	v_mad_i64_i32 v[114:115], s[0:1], v164, s46, v[120:121]
	v_lshl_add_u64 v[114:115], v[114:115], 0, v[122:123]
	s_nop 0
	v_fmamk_f32 v107, v236, 0x3a800000, v154
	v_mul_f32_e32 v116, 0x4b800000, v107
	v_cmp_gt_f32_e32 vcc, s45, v107
	s_nop 1
	v_cndmask_b32_e32 v107, v107, v116, vcc
	v_rsq_f32_e32 v118, v107
	v_ashrrev_i32_e32 v107, 31, v106
	v_lshl_add_u64 v[116:117], v[106:107], 2, s[10:11]
	v_mul_f32_e32 v107, 0x45800000, v118
	v_cndmask_b32_e32 v118, v118, v107, vcc
	v_pk_mul_f32 v[98:99], v[98:99], v[118:119] op_sel_hi:[1,0]
	v_pk_mul_f32 v[112:113], v[112:113], v[118:119] op_sel_hi:[1,0]
	v_pk_mul_f32 v[100:101], v[100:101], v[118:119] op_sel_hi:[1,0]
	v_pk_mul_f32 v[108:109], v[108:109], v[118:119] op_sel_hi:[1,0]
	v_pk_mul_f32 v[102:103], v[102:103], v[118:119] op_sel_hi:[1,0]
	v_pk_mul_f32 v[110:111], v[110:111], v[118:119] op_sel_hi:[1,0]
	v_pk_mul_f32 v[96:97], v[96:97], v[118:119] op_sel_hi:[1,0]
	v_pk_mul_f32 v[104:105], v[104:105], v[118:119] op_sel_hi:[1,0]
	v_mul_f32_e32 v145, 0xbfb8aa3b, v99
	v_mul_f32_e32 v107, 0xbfb8aa3b, v113
	v_mul_f32_e32 v118, 0xbfb8aa3b, v101
	v_mul_f32_e32 v119, 0xbfb8aa3b, v109
	v_mul_f32_e32 v124, 0xbfb8aa3b, v103
	v_mul_f32_e32 v125, 0xbfb8aa3b, v111
	v_mul_f32_e32 v126, 0xbfb8aa3b, v97
	v_mul_f32_e32 v127, 0xbfb8aa3b, v105
	v_exp_f32_e32 v145, v145
	v_exp_f32_e32 v107, v107
	v_exp_f32_e32 v118, v118
	v_exp_f32_e32 v119, v119
	v_exp_f32_e32 v124, v124
	v_exp_f32_e32 v125, v125
	v_exp_f32_e32 v126, v126
	v_exp_f32_e32 v127, v127
	v_add_f32_e32 v145, 1.0, v145
	v_add_f32_e32 v107, 1.0, v107
	v_add_f32_e32 v118, 1.0, v118
	v_add_f32_e32 v119, 1.0, v119
	v_add_f32_e32 v124, 1.0, v124
	v_add_f32_e32 v125, 1.0, v125
	v_add_f32_e32 v126, 1.0, v126
	v_add_f32_e32 v127, 1.0, v127
	v_rcp_f32_e32 v145, v145
	v_rcp_f32_e32 v107, v107
	v_rcp_f32_e32 v118, v118
; __device__ __forceinline__ unsigned pk2(float lo, float hi) { return pg8::cvt_pk_bf16(lo, hi); }
; __device__ __forceinline__ float silu_f(float x) { return x * sigmoid_f(x); }
;     __device__ __forceinline__ void operator()(const f32x4 (&acc)[2][2][4][2], const pg8::Unit& u, int wr, int wc, int fr, int fq) const {
;         const int row0 = u.pm * 256 + wr * 64 + fr, col = u.pn * 128 + wc * 32 + 8 * fq;
; #pragma unroll
;         for (int ai = 0; ai < 2; ++ai)
; #pragma unroll
;             for (int m = 0; m < 4; ++m) {
;                 const int row = row0 + ai * 128 + m * 16;
;                 const float rs = sumsq ? rsqrtf(sumsq[row] * (1.f / 1024.f) + EPS) : 1.f;
;                 float o[8];
; #pragma unroll
;                 for (int n = 0; n < 2; ++n)
; #pragma unroll
;                     for (int e = 0; e < 4; ++e) { const float g = acc[ai][0][m][n][e] * rs, up = acc[ai][1][m][n][e] * rs; o[4 * n + e] = silu_f(g) * up; }
;                 u32x4 w; w.x = pk2(o[0], o[1]); w.y = pk2(o[2], o[3]); w.z = pk2(o[4], o[5]); w.w = pk2(o[6], o[7]);
;                 *(u32x4*)(H + (size_t)row * DFF + col) = w;
	v_rcp_f32_e32 v119, v119
	v_rcp_f32_e32 v124, v124
	v_rcp_f32_e32 v125, v125
	v_rcp_f32_e32 v126, v126
	v_rcp_f32_e32 v127, v127
	v_mul_f32_e32 v99, v99, v145
	v_mul_f32_e32 v107, v113, v107
	v_mul_f32_e32 v101, v101, v118
	v_mul_f32_e32 v109, v109, v119
	v_mul_f32_e32 v103, v103, v124
	v_mul_f32_e32 v111, v111, v125
	v_mul_f32_e32 v97, v97, v126
	v_mul_f32_e32 v105, v105, v127
	v_mul_f32_e32 v99, v98, v99
	v_mul_f32_e32 v107, v112, v107
	v_mul_f32_e32 v100, v100, v101
	v_mul_f32_e32 v101, v108, v109
	v_mul_f32_e32 v102, v102, v103
	v_mul_f32_e32 v103, v110, v111
	v_mul_f32_e32 v108, v96, v97
	v_mul_f32_e32 v104, v104, v105
	v_cvt_pk_bf16_f32 v96, v107, v100
	v_cvt_pk_bf16_f32 v97, v101, v102
	v_cvt_pk_bf16_f32 v98, v103, v108
	v_cvt_pk_bf16_f32 v99, v104, v99
	global_store_dwordx4 v[114:115], v[96:99], off
	s_nop 0
	s_nop 0
	v_mov_b32_e32 v97, v84
	v_mov_b32_e32 v84, v93
	v_mov_b32_e32 v93, v86
	v_mov_b32_e32 v86, v95
	v_mov_b32_e32 v95, v80
	v_mov_b32_e32 v80, v89
	v_mov_b32_e32 v89, v82
	v_mov_b32_e32 v82, v91
	v_mov_b32_e32 v96, v92
	v_mov_b32_e32 v92, v94
	v_mov_b32_e32 v94, v88
	v_mov_b32_e32 v88, v90
	v_or_b32_e32 v90, 48, v144
	v_mad_i64_i32 v[98:99], s[0:1], v106, s46, v[120:121]
	v_lshl_add_u64 v[98:99], v[98:99], 0, v[122:123]
	s_nop 0
	v_fmamk_f32 v91, v237, 0x3a800000, v154
	v_mul_f32_e32 v100, 0x4b800000, v91
	v_cmp_gt_f32_e32 vcc, s45, v91
	s_nop 1
	v_cndmask_b32_e32 v91, v91, v100, vcc
	v_rsq_f32_e32 v102, v91
	v_ashrrev_i32_e32 v91, 31, v90
	v_lshl_add_u64 v[100:101], v[90:91], 2, s[10:11]
	v_mul_f32_e32 v91, 0x45800000, v102
	v_cndmask_b32_e32 v102, v102, v91, vcc
	v_pk_mul_f32 v[82:83], v[82:83], v[102:103] op_sel_hi:[1,0]
	v_pk_mul_f32 v[96:97], v[96:97], v[102:103] op_sel_hi:[1,0]
	v_pk_mul_f32 v[84:85], v[84:85], v[102:103] op_sel_hi:[1,0]
	v_pk_mul_f32 v[92:93], v[92:93], v[102:103] op_sel_hi:[1,0]
	v_pk_mul_f32 v[86:87], v[86:87], v[102:103] op_sel_hi:[1,0]
	v_pk_mul_f32 v[94:95], v[94:95], v[102:103] op_sel_hi:[1,0]
	v_pk_mul_f32 v[80:81], v[80:81], v[102:103] op_sel_hi:[1,0]
	v_pk_mul_f32 v[88:89], v[88:89], v[102:103] op_sel_hi:[1,0]
	v_mul_f32_e32 v108, 0xbfb8aa3b, v83
	v_mul_f32_e32 v91, 0xbfb8aa3b, v97
	v_mul_f32_e32 v102, 0xbfb8aa3b, v85
	v_mul_f32_e32 v103, 0xbfb8aa3b, v93
	v_mul_f32_e32 v104, 0xbfb8aa3b, v87
	v_mul_f32_e32 v105, 0xbfb8aa3b, v95
	v_mul_f32_e32 v106, 0xbfb8aa3b, v81
	v_mul_f32_e32 v107, 0xbfb8aa3b, v89
	v_exp_f32_e32 v108, v108
	v_exp_f32_e32 v91, v91
	v_exp_f32_e32 v102, v102
	v_exp_f32_e32 v103, v103
	v_exp_f32_e32 v104, v104
	v_exp_f32_e32 v105, v105
	v_exp_f32_e32 v106, v106
	v_exp_f32_e32 v107, v107
	v_add_f32_e32 v108, 1.0, v108
	v_add_f32_e32 v91, 1.0, v91
	v_add_f32_e32 v102, 1.0, v102
	v_add_f32_e32 v103, 1.0, v103
	v_add_f32_e32 v104, 1.0, v104
	v_add_f32_e32 v105, 1.0, v105
	v_add_f32_e32 v106, 1.0, v106
	v_add_f32_e32 v107, 1.0, v107
	v_rcp_f32_e32 v108, v108
	v_rcp_f32_e32 v91, v91
	v_rcp_f32_e32 v102, v102
	v_rcp_f32_e32 v103, v103
	v_rcp_f32_e32 v104, v104
	v_rcp_f32_e32 v105, v105
	v_rcp_f32_e32 v106, v106
	v_rcp_f32_e32 v107, v107
	v_mul_f32_e32 v83, v83, v108
	v_mul_f32_e32 v91, v97, v91
	v_mul_f32_e32 v85, v85, v102
	v_mul_f32_e32 v93, v93, v103
	v_mul_f32_e32 v87, v87, v104
	v_mul_f32_e32 v95, v95, v105
	v_mul_f32_e32 v81, v81, v106
	v_mul_f32_e32 v89, v89, v107
	v_mul_f32_e32 v83, v82, v83
	v_mul_f32_e32 v91, v96, v91
	v_mul_f32_e32 v84, v84, v85
	v_mul_f32_e32 v85, v92, v93
	v_mul_f32_e32 v86, v86, v87
	v_mul_f32_e32 v87, v94, v95
	v_mul_f32_e32 v92, v80, v81
	v_mul_f32_e32 v88, v88, v89
	v_cvt_pk_bf16_f32 v80, v91, v84
	v_cvt_pk_bf16_f32 v81, v85, v86
	v_cvt_pk_bf16_f32 v82, v87, v92
	v_cvt_pk_bf16_f32 v83, v88, v83
	global_store_dwordx4 v[98:99], v[80:83], off
	s_nop 0
	s_nop 0
	v_mov_b32_e32 v80, v76
	v_mov_b32_e32 v76, v78
	v_mov_b32_e32 v78, v68
	v_mov_b32_e32 v68, v70
	v_mov_b32_e32 v81, v72
	v_mov_b32_e32 v72, v77
	v_mov_b32_e32 v77, v74
	v_mov_b32_e32 v74, v79
	v_mov_b32_e32 v79, v64
	v_mov_b32_e32 v64, v69
	v_mov_b32_e32 v69, v66
	v_mov_b32_e32 v66, v71
	s_nop 0
	v_fmamk_f32 v70, v238, 0x3a800000, v154
	v_mul_f32_e32 v71, 0x4b800000, v70
	v_cmp_gt_f32_e32 vcc, s45, v70
	s_nop 1
	v_cndmask_b32_e32 v70, v70, v71, vcc
	v_rsq_f32_e32 v82, v70
	v_mad_i64_i32 v[70:71], s[0:1], v90, s46, v[120:121]
	v_lshl_add_u64 v[70:71], v[70:71], 0, v[122:123]
	v_mul_f32_e32 v83, 0x45800000, v82
	v_cndmask_b32_e32 v82, v82, v83, vcc
	v_pk_mul_f32 v[66:67], v[66:67], v[82:83] op_sel_hi:[1,0]
	v_pk_mul_f32 v[80:81], v[80:81], v[82:83] op_sel_hi:[1,0]
	v_pk_mul_f32 v[72:73], v[72:73], v[82:83] op_sel_hi:[1,0]
	v_pk_mul_f32 v[76:77], v[76:77], v[82:83] op_sel_hi:[1,0]
	v_pk_mul_f32 v[74:75], v[74:75], v[82:83] op_sel_hi:[1,0]
	v_pk_mul_f32 v[78:79], v[78:79], v[82:83] op_sel_hi:[1,0]
	v_pk_mul_f32 v[64:65], v[64:65], v[82:83] op_sel_hi:[1,0]
	v_pk_mul_f32 v[68:69], v[68:69], v[82:83] op_sel_hi:[1,0]
	v_mul_f32_e32 v89, 0xbfb8aa3b, v67
	v_mul_f32_e32 v82, 0xbfb8aa3b, v81
	v_mul_f32_e32 v83, 0xbfb8aa3b, v73
	v_mul_f32_e32 v84, 0xbfb8aa3b, v77
	v_mul_f32_e32 v85, 0xbfb8aa3b, v75
	v_mul_f32_e32 v86, 0xbfb8aa3b, v79
	v_mul_f32_e32 v87, 0xbfb8aa3b, v65
	v_mul_f32_e32 v88, 0xbfb8aa3b, v69
	v_exp_f32_e32 v89, v89
	v_exp_f32_e32 v82, v82
	v_exp_f32_e32 v83, v83
	v_exp_f32_e32 v84, v84
	v_exp_f32_e32 v85, v85
	v_exp_f32_e32 v86, v86
	v_exp_f32_e32 v87, v87
	v_exp_f32_e32 v88, v88
	v_add_f32_e32 v89, 1.0, v89
	v_add_f32_e32 v82, 1.0, v82
	v_add_f32_e32 v83, 1.0, v83
	v_add_f32_e32 v84, 1.0, v84
	v_add_f32_e32 v85, 1.0, v85
	v_add_f32_e32 v86, 1.0, v86
	v_add_f32_e32 v87, 1.0, v87
	v_add_f32_e32 v88, 1.0, v88
	v_rcp_f32_e32 v89, v89
	v_rcp_f32_e32 v82, v82
	v_rcp_f32_e32 v83, v83
; __device__ __forceinline__ unsigned pk2(float lo, float hi) { return pg8::cvt_pk_bf16(lo, hi); }
; __device__ __forceinline__ float silu_f(float x) { return x * sigmoid_f(x); }
;     __device__ __forceinline__ void operator()(const f32x4 (&acc)[2][2][4][2], const pg8::Unit& u, int wr, int wc, int fr, int fq) const {
;         const int row0 = u.pm * 256 + wr * 64 + fr, col = u.pn * 128 + wc * 32 + 8 * fq;
; #pragma unroll
;         for (int ai = 0; ai < 2; ++ai)
; #pragma unroll
;             for (int m = 0; m < 4; ++m) {
;                 const int row = row0 + ai * 128 + m * 16;
;                 const float rs = sumsq ? rsqrtf(sumsq[row] * (1.f / 1024.f) + EPS) : 1.f;
;                 float o[8];
; #pragma unroll
;                 for (int n = 0; n < 2; ++n)
; #pragma unroll
;                     for (int e = 0; e < 4; ++e) { const float g = acc[ai][0][m][n][e] * rs, up = acc[ai][1][m][n][e] * rs; o[4 * n + e] = silu_f(g) * up; }
;                 u32x4 w; w.x = pk2(o[0], o[1]); w.y = pk2(o[2], o[3]); w.z = pk2(o[4], o[5]); w.w = pk2(o[6], o[7]);
;                 *(u32x4*)(H + (size_t)row * DFF + col) = w;
	v_rcp_f32_e32 v84, v84
	v_rcp_f32_e32 v85, v85
	v_rcp_f32_e32 v86, v86
	v_rcp_f32_e32 v87, v87
	v_rcp_f32_e32 v88, v88
	v_mul_f32_e32 v67, v67, v89
	v_mul_f32_e32 v81, v81, v82
	v_mul_f32_e32 v73, v73, v83
	v_mul_f32_e32 v77, v77, v84
	v_mul_f32_e32 v75, v75, v85
	v_mul_f32_e32 v79, v79, v86
	v_mul_f32_e32 v65, v65, v87
	v_mul_f32_e32 v69, v69, v88
	v_mul_f32_e32 v67, v66, v67
	v_mul_f32_e32 v80, v80, v81
	v_mul_f32_e32 v72, v72, v73
	v_mul_f32_e32 v73, v76, v77
	v_mul_f32_e32 v74, v74, v75
	v_mul_f32_e32 v75, v78, v79
	v_mul_f32_e32 v76, v64, v65
	v_mul_f32_e32 v68, v68, v69
	v_cvt_pk_bf16_f32 v64, v80, v72
	v_cvt_pk_bf16_f32 v65, v73, v74
	v_cvt_pk_bf16_f32 v66, v75, v76
	v_cvt_pk_bf16_f32 v67, v68, v67
	global_store_dwordx4 v[70:71], v[64:67], off
	s_nop 0
	s_nop 0
	v_mov_b32_e32 v65, v56
	v_mov_b32_e32 v56, v61
	v_mov_b32_e32 v61, v58
	v_mov_b32_e32 v58, v63
	v_mov_b32_e32 v63, v48
	v_mov_b32_e32 v48, v53
	v_mov_b32_e32 v53, v50
	v_mov_b32_e32 v50, v55
	v_mov_b32_e32 v64, v60
	v_mov_b32_e32 v60, v62
	v_mov_b32_e32 v62, v52
	v_mov_b32_e32 v52, v54
	v_add_u32_e32 v54, 0x80, v144
	s_nop 0
	v_fmamk_f32 v55, v239, 0x3a800000, v154
	v_mul_f32_e32 v66, 0x4b800000, v55
	v_cmp_gt_f32_e32 vcc, s45, v55
	s_nop 1
	v_cndmask_b32_e32 v55, v55, v66, vcc
	v_rsq_f32_e32 v66, v55
	v_mad_i64_i32 v[54:55], s[0:1], v54, s46, v[120:121]
	v_lshl_add_u64 v[54:55], v[54:55], 0, v[122:123]
	v_mul_f32_e32 v67, 0x45800000, v66
	v_cndmask_b32_e32 v66, v66, v67, vcc
	v_pk_mul_f32 v[50:51], v[50:51], v[66:67] op_sel_hi:[1,0]
	v_pk_mul_f32 v[64:65], v[64:65], v[66:67] op_sel_hi:[1,0]
	v_pk_mul_f32 v[56:57], v[56:57], v[66:67] op_sel_hi:[1,0]
	v_pk_mul_f32 v[60:61], v[60:61], v[66:67] op_sel_hi:[1,0]
	v_pk_mul_f32 v[58:59], v[58:59], v[66:67] op_sel_hi:[1,0]
	v_pk_mul_f32 v[62:63], v[62:63], v[66:67] op_sel_hi:[1,0]
	v_pk_mul_f32 v[48:49], v[48:49], v[66:67] op_sel_hi:[1,0]
	v_pk_mul_f32 v[52:53], v[52:53], v[66:67] op_sel_hi:[1,0]
	v_mul_f32_e32 v73, 0xbfb8aa3b, v51
	v_mul_f32_e32 v66, 0xbfb8aa3b, v65
	v_mul_f32_e32 v67, 0xbfb8aa3b, v57
	v_mul_f32_e32 v68, 0xbfb8aa3b, v61
	v_mul_f32_e32 v69, 0xbfb8aa3b, v59
	v_mul_f32_e32 v70, 0xbfb8aa3b, v63
	v_mul_f32_e32 v71, 0xbfb8aa3b, v49
	v_mul_f32_e32 v72, 0xbfb8aa3b, v53
	v_exp_f32_e32 v73, v73
	v_exp_f32_e32 v66, v66
	v_exp_f32_e32 v67, v67
	v_exp_f32_e32 v68, v68
	v_exp_f32_e32 v69, v69
	v_exp_f32_e32 v70, v70
	v_exp_f32_e32 v71, v71
	v_exp_f32_e32 v72, v72
	v_add_f32_e32 v73, 1.0, v73
	v_add_f32_e32 v66, 1.0, v66
	v_add_f32_e32 v67, 1.0, v67
	v_add_f32_e32 v68, 1.0, v68
	v_add_f32_e32 v69, 1.0, v69
	v_add_f32_e32 v70, 1.0, v70
	v_add_f32_e32 v71, 1.0, v71
	v_add_f32_e32 v72, 1.0, v72
	v_rcp_f32_e32 v73, v73
	v_rcp_f32_e32 v66, v66
	v_rcp_f32_e32 v67, v67
	v_rcp_f32_e32 v68, v68
	v_rcp_f32_e32 v69, v69
	v_rcp_f32_e32 v70, v70
	v_rcp_f32_e32 v71, v71
	v_rcp_f32_e32 v72, v72
	v_mul_f32_e32 v51, v51, v73
	v_mul_f32_e32 v65, v65, v66
	v_mul_f32_e32 v57, v57, v67
	v_mul_f32_e32 v61, v61, v68
	v_mul_f32_e32 v59, v59, v69
	v_mul_f32_e32 v63, v63, v70
	v_mul_f32_e32 v49, v49, v71
	v_mul_f32_e32 v53, v53, v72
	v_mul_f32_e32 v51, v50, v51
	v_mul_f32_e32 v64, v64, v65
	v_mul_f32_e32 v56, v56, v57
	v_mul_f32_e32 v57, v60, v61
	v_mul_f32_e32 v58, v58, v59
	v_mul_f32_e32 v59, v62, v63
	v_mul_f32_e32 v60, v48, v49
	v_mul_f32_e32 v52, v52, v53
	v_cvt_pk_bf16_f32 v48, v64, v56
	v_cvt_pk_bf16_f32 v49, v57, v58
	v_cvt_pk_bf16_f32 v50, v59, v60
	v_cvt_pk_bf16_f32 v51, v52, v51
	global_store_dwordx4 v[54:55], v[48:51], off
	s_nop 0
	s_nop 0
	v_mov_b32_e32 v49, v40
	v_mov_b32_e32 v40, v45
	v_mov_b32_e32 v45, v42
	v_mov_b32_e32 v42, v47
	v_mov_b32_e32 v47, v32
	v_mov_b32_e32 v32, v37
	v_mov_b32_e32 v37, v34
	v_mov_b32_e32 v34, v39
	v_mov_b32_e32 v48, v44
	v_mov_b32_e32 v44, v46
	v_mov_b32_e32 v46, v36
	v_mov_b32_e32 v36, v38
	v_add_u32_e32 v38, 0x90, v144
	s_nop 0
	v_fmamk_f32 v39, v240, 0x3a800000, v154
	v_mul_f32_e32 v50, 0x4b800000, v39
	v_cmp_gt_f32_e32 vcc, s45, v39
	s_nop 1
	v_cndmask_b32_e32 v39, v39, v50, vcc
	v_rsq_f32_e32 v50, v39
	v_mad_i64_i32 v[38:39], s[0:1], v38, s46, v[120:121]
	v_lshl_add_u64 v[38:39], v[38:39], 0, v[122:123]
	v_mul_f32_e32 v51, 0x45800000, v50
	v_cndmask_b32_e32 v50, v50, v51, vcc
	v_pk_mul_f32 v[34:35], v[34:35], v[50:51] op_sel_hi:[1,0]
	v_pk_mul_f32 v[48:49], v[48:49], v[50:51] op_sel_hi:[1,0]
	v_pk_mul_f32 v[40:41], v[40:41], v[50:51] op_sel_hi:[1,0]
	v_pk_mul_f32 v[44:45], v[44:45], v[50:51] op_sel_hi:[1,0]
	v_pk_mul_f32 v[42:43], v[42:43], v[50:51] op_sel_hi:[1,0]
	v_pk_mul_f32 v[46:47], v[46:47], v[50:51] op_sel_hi:[1,0]
	v_pk_mul_f32 v[32:33], v[32:33], v[50:51] op_sel_hi:[1,0]
	v_pk_mul_f32 v[36:37], v[36:37], v[50:51] op_sel_hi:[1,0]
	v_mul_f32_e32 v57, 0xbfb8aa3b, v35
	v_mul_f32_e32 v50, 0xbfb8aa3b, v49
	v_mul_f32_e32 v51, 0xbfb8aa3b, v41
	v_mul_f32_e32 v52, 0xbfb8aa3b, v45
	v_mul_f32_e32 v53, 0xbfb8aa3b, v43
	v_mul_f32_e32 v54, 0xbfb8aa3b, v47
	v_mul_f32_e32 v55, 0xbfb8aa3b, v33
	v_mul_f32_e32 v56, 0xbfb8aa3b, v37
	v_exp_f32_e32 v57, v57
	v_exp_f32_e32 v50, v50
	v_exp_f32_e32 v51, v51
	v_exp_f32_e32 v52, v52
	v_exp_f32_e32 v53, v53
	v_exp_f32_e32 v54, v54
	v_exp_f32_e32 v55, v55
	v_exp_f32_e32 v56, v56
	v_add_f32_e32 v57, 1.0, v57
	v_add_f32_e32 v50, 1.0, v50
	v_add_f32_e32 v51, 1.0, v51
	v_add_f32_e32 v52, 1.0, v52
	v_add_f32_e32 v53, 1.0, v53
	v_add_f32_e32 v54, 1.0, v54
	v_add_f32_e32 v55, 1.0, v55
	v_add_f32_e32 v56, 1.0, v56
	v_rcp_f32_e32 v57, v57
	v_rcp_f32_e32 v50, v50
	v_rcp_f32_e32 v51, v51
	v_rcp_f32_e32 v52, v52
	v_rcp_f32_e32 v53, v53
	v_rcp_f32_e32 v54, v54
	v_rcp_f32_e32 v55, v55
	v_rcp_f32_e32 v56, v56
	v_mul_f32_e32 v35, v35, v57
	v_mul_f32_e32 v49, v49, v50
	v_mul_f32_e32 v41, v41, v51
; #define PG8_BAR __builtin_amdgcn_s_barrier()
; __device__ __forceinline__ unsigned pk2(float lo, float hi) { return pg8::cvt_pk_bf16(lo, hi); }
; __device__ __forceinline__ float silu_f(float x) { return x * sigmoid_f(x); }
; template <class Epi, class Sched, bool ALIGN_EPI = false, bool SP2 = false>
; __device__ __forceinline__ void gemm_phase(PG8_LAS unsigned char* lds, const Gemm g, const Sched& S, const Epi& E) {
;     ...
;         if (!has_next) break;
; #pragma unroll
;         for (int a = 0; a < 2; ++a)
; #pragma unroll
;             for (int b = 0; b < 2; ++b)
; #pragma unroll
;                 for (int m = 0; m < 4; ++m)
; #pragma unroll
;                     for (int n = 0; n < 2; ++n) acc[a][b][m][n] = (f32x4){0.f, 0.f, 0.f, 0.f};
;         cur = nxt; cA = nA; cB = nB; ++ui;
;         if constexpr (ALIGN_EPI) { if (wr == 1) PG8_BAR; }
;     __device__ __forceinline__ void operator()(const f32x4 (&acc)[2][2][4][2], const pg8::Unit& u, int wr, int wc, int fr, int fq) const {
;     ...
;                 const int row = row0 + ai * 128 + m * 16;
;                 const float rs = sumsq ? rsqrtf(sumsq[row] * (1.f / 1024.f) + EPS) : 1.f;
;                 float o[8];
; #pragma unroll
;                 for (int n = 0; n < 2; ++n)
; #pragma unroll
;                     for (int e = 0; e < 4; ++e) { const float g = acc[ai][0][m][n][e] * rs, up = acc[ai][1][m][n][e] * rs; o[4 * n + e] = silu_f(g) * up; }
;                 u32x4 w; w.x = pk2(o[0], o[1]); w.y = pk2(o[2], o[3]); w.z = pk2(o[4], o[5]); w.w = pk2(o[6], o[7]);
;                 *(u32x4*)(H + (size_t)row * DFF + col) = w;
	v_mul_f32_e32 v45, v45, v52
	v_mul_f32_e32 v43, v43, v53
	v_mul_f32_e32 v47, v47, v54
	v_mul_f32_e32 v33, v33, v55
	v_mul_f32_e32 v37, v37, v56
	v_mul_f32_e32 v35, v34, v35
	v_mul_f32_e32 v48, v48, v49
	v_mul_f32_e32 v40, v40, v41
	v_mul_f32_e32 v41, v44, v45
	v_mul_f32_e32 v42, v42, v43
	v_mul_f32_e32 v43, v46, v47
	v_mul_f32_e32 v44, v32, v33
	v_mul_f32_e32 v36, v36, v37
	v_cvt_pk_bf16_f32 v32, v48, v40
	v_cvt_pk_bf16_f32 v33, v41, v42
	v_cvt_pk_bf16_f32 v34, v43, v44
	v_cvt_pk_bf16_f32 v35, v36, v35
	global_store_dwordx4 v[38:39], v[32:35], off
	s_nop 0
	s_nop 0
	v_mov_b32_e32 v33, v24
	v_mov_b32_e32 v24, v29
	v_mov_b32_e32 v29, v26
	v_mov_b32_e32 v26, v31
	v_mov_b32_e32 v31, v16
	v_mov_b32_e32 v16, v21
	v_mov_b32_e32 v21, v18
	v_mov_b32_e32 v18, v23
	v_mov_b32_e32 v32, v28
	v_mov_b32_e32 v28, v30
	v_mov_b32_e32 v30, v20
	v_mov_b32_e32 v20, v22
	v_add_u32_e32 v22, 0xa0, v144
	s_nop 0
	v_fmamk_f32 v23, v241, 0x3a800000, v154
	v_mul_f32_e32 v34, 0x4b800000, v23
	v_cmp_gt_f32_e32 vcc, s45, v23
	s_nop 1
	v_cndmask_b32_e32 v23, v23, v34, vcc
	v_rsq_f32_e32 v34, v23
	v_mad_i64_i32 v[22:23], s[0:1], v22, s46, v[120:121]
	v_lshl_add_u64 v[22:23], v[22:23], 0, v[122:123]
	v_mul_f32_e32 v35, 0x45800000, v34
	v_cndmask_b32_e32 v34, v34, v35, vcc
	v_pk_mul_f32 v[18:19], v[18:19], v[34:35] op_sel_hi:[1,0]
	v_pk_mul_f32 v[32:33], v[32:33], v[34:35] op_sel_hi:[1,0]
	v_pk_mul_f32 v[24:25], v[24:25], v[34:35] op_sel_hi:[1,0]
	v_pk_mul_f32 v[28:29], v[28:29], v[34:35] op_sel_hi:[1,0]
	v_pk_mul_f32 v[26:27], v[26:27], v[34:35] op_sel_hi:[1,0]
	v_pk_mul_f32 v[30:31], v[30:31], v[34:35] op_sel_hi:[1,0]
	v_pk_mul_f32 v[16:17], v[16:17], v[34:35] op_sel_hi:[1,0]
	v_pk_mul_f32 v[20:21], v[20:21], v[34:35] op_sel_hi:[1,0]
	v_mul_f32_e32 v41, 0xbfb8aa3b, v19
	v_mul_f32_e32 v34, 0xbfb8aa3b, v33
	v_mul_f32_e32 v35, 0xbfb8aa3b, v25
	v_mul_f32_e32 v36, 0xbfb8aa3b, v29
	v_mul_f32_e32 v37, 0xbfb8aa3b, v27
	v_mul_f32_e32 v38, 0xbfb8aa3b, v31
	v_mul_f32_e32 v39, 0xbfb8aa3b, v17
	v_mul_f32_e32 v40, 0xbfb8aa3b, v21
	v_exp_f32_e32 v41, v41
	v_exp_f32_e32 v34, v34
	v_exp_f32_e32 v35, v35
	v_exp_f32_e32 v36, v36
	v_exp_f32_e32 v37, v37
	v_exp_f32_e32 v38, v38
	v_exp_f32_e32 v39, v39
	v_exp_f32_e32 v40, v40
	v_add_f32_e32 v41, 1.0, v41
	v_add_f32_e32 v34, 1.0, v34
	v_add_f32_e32 v35, 1.0, v35
	v_add_f32_e32 v36, 1.0, v36
	v_add_f32_e32 v37, 1.0, v37
	v_add_f32_e32 v38, 1.0, v38
	v_add_f32_e32 v39, 1.0, v39
	v_add_f32_e32 v40, 1.0, v40
	v_rcp_f32_e32 v41, v41
	v_rcp_f32_e32 v34, v34
	v_rcp_f32_e32 v35, v35
	v_rcp_f32_e32 v36, v36
	v_rcp_f32_e32 v37, v37
	v_rcp_f32_e32 v38, v38
	v_rcp_f32_e32 v39, v39
	v_rcp_f32_e32 v40, v40
	v_mul_f32_e32 v19, v19, v41
	v_mul_f32_e32 v33, v33, v34
	v_mul_f32_e32 v25, v25, v35
	v_mul_f32_e32 v29, v29, v36
	v_mul_f32_e32 v27, v27, v37
	v_mul_f32_e32 v31, v31, v38
	v_mul_f32_e32 v17, v17, v39
	v_mul_f32_e32 v21, v21, v40
	v_mul_f32_e32 v19, v18, v19
	v_mul_f32_e32 v32, v32, v33
	v_mul_f32_e32 v24, v24, v25
	v_mul_f32_e32 v25, v28, v29
	v_mul_f32_e32 v26, v26, v27
	v_mul_f32_e32 v27, v30, v31
	v_mul_f32_e32 v28, v16, v17
	v_mul_f32_e32 v20, v20, v21
	v_cvt_pk_bf16_f32 v16, v32, v24
	v_cvt_pk_bf16_f32 v17, v25, v26
	v_cvt_pk_bf16_f32 v18, v27, v28
	v_cvt_pk_bf16_f32 v19, v20, v19
	global_store_dwordx4 v[22:23], v[16:19], off
	s_nop 0
	s_andn2_b64 vcc, exec, s[4:5]
	v_mov_b32_e32 v17, v8
	v_mov_b32_e32 v8, v13
	v_mov_b32_e32 v13, v10
	v_mov_b32_e32 v10, v15
	v_mov_b32_e32 v15, v0
	v_mov_b32_e32 v0, v5
	v_mov_b32_e32 v5, v2
	v_mov_b32_e32 v2, v7
	v_mov_b32_e32 v16, v12
	v_mov_b32_e32 v12, v14
	v_mov_b32_e32 v14, v4
	v_mov_b32_e32 v4, v6
	v_add_u32_e32 v6, 0xb0, v144
	s_nop 0
	v_fmamk_f32 v7, v242, 0x3a800000, v154
	v_mul_f32_e32 v18, 0x4b800000, v7
	v_cmp_gt_f32_e64 s[0:1], s45, v7
	s_nop 1
	v_cndmask_b32_e64 v7, v7, v18, s[0:1]
	v_rsq_f32_e32 v18, v7
	v_mad_i64_i32 v[6:7], s[22:23], v6, s46, v[120:121]
	v_lshl_add_u64 v[6:7], v[6:7], 0, v[122:123]
	v_mul_f32_e32 v19, 0x45800000, v18
	v_cndmask_b32_e64 v18, v18, v19, s[0:1]
	v_pk_mul_f32 v[2:3], v[2:3], v[18:19] op_sel_hi:[1,0]
	v_pk_mul_f32 v[16:17], v[16:17], v[18:19] op_sel_hi:[1,0]
	v_pk_mul_f32 v[8:9], v[8:9], v[18:19] op_sel_hi:[1,0]
	v_pk_mul_f32 v[12:13], v[12:13], v[18:19] op_sel_hi:[1,0]
	v_pk_mul_f32 v[10:11], v[10:11], v[18:19] op_sel_hi:[1,0]
	v_pk_mul_f32 v[14:15], v[14:15], v[18:19] op_sel_hi:[1,0]
	v_pk_mul_f32 v[0:1], v[0:1], v[18:19] op_sel_hi:[1,0]
	v_pk_mul_f32 v[4:5], v[4:5], v[18:19] op_sel_hi:[1,0]
	v_mul_f32_e32 v25, 0xbfb8aa3b, v3
	v_mul_f32_e32 v18, 0xbfb8aa3b, v17
	v_mul_f32_e32 v19, 0xbfb8aa3b, v9
	v_mul_f32_e32 v20, 0xbfb8aa3b, v13
	v_mul_f32_e32 v21, 0xbfb8aa3b, v11
	v_mul_f32_e32 v22, 0xbfb8aa3b, v15
	v_mul_f32_e32 v23, 0xbfb8aa3b, v1
	v_mul_f32_e32 v24, 0xbfb8aa3b, v5
	v_exp_f32_e32 v25, v25
	v_exp_f32_e32 v18, v18
	v_exp_f32_e32 v19, v19
	v_exp_f32_e32 v20, v20
	v_exp_f32_e32 v21, v21
	v_exp_f32_e32 v22, v22
	v_exp_f32_e32 v23, v23
	v_exp_f32_e32 v24, v24
	v_add_f32_e32 v25, 1.0, v25
	v_add_f32_e32 v18, 1.0, v18
	v_add_f32_e32 v19, 1.0, v19
	v_add_f32_e32 v20, 1.0, v20
	v_add_f32_e32 v21, 1.0, v21
	v_add_f32_e32 v22, 1.0, v22
	v_add_f32_e32 v23, 1.0, v23
	v_add_f32_e32 v24, 1.0, v24
	v_rcp_f32_e32 v25, v25
	v_rcp_f32_e32 v18, v18
	v_rcp_f32_e32 v19, v19
	v_rcp_f32_e32 v20, v20
	v_rcp_f32_e32 v21, v21
	v_rcp_f32_e32 v22, v22
	v_rcp_f32_e32 v23, v23
	v_rcp_f32_e32 v24, v24
	v_mul_f32_e32 v3, v3, v25
	v_mul_f32_e32 v17, v17, v18
	v_mul_f32_e32 v9, v9, v19
	v_mul_f32_e32 v13, v13, v20
	v_mul_f32_e32 v11, v11, v21
	v_mul_f32_e32 v15, v15, v22
	v_mul_f32_e32 v1, v1, v23
	v_mul_f32_e32 v5, v5, v24
	v_mul_f32_e32 v3, v2, v3
	s_mov_b64 s[0:1], -1
	v_mul_f32_e32 v16, v16, v17
	v_mul_f32_e32 v8, v8, v9
	v_mul_f32_e32 v9, v12, v13
	v_mul_f32_e32 v10, v10, v11
	v_mul_f32_e32 v11, v14, v15
	v_mul_f32_e32 v12, v0, v1
	v_mul_f32_e32 v4, v4, v5
	v_cvt_pk_bf16_f32 v0, v16, v8
	v_cvt_pk_bf16_f32 v1, v9, v10
	v_cvt_pk_bf16_f32 v2, v11, v12
	v_cvt_pk_bf16_f32 v3, v4, v3
	global_store_dwordx4 v[6:7], v[0:3], off
	s_cbranch_vccnz .LBB0_778
	s_andn2_b64 vcc, exec, s[2:3]
	s_cbranch_vccnz .LBB0_777
	s_barrier
	s_branch .LBB0_777
